# combo24 + E65: ssd_pass2 epilogue issues its small skip-weight load before the 64 KB Z-gate tile loads and waits for it alone; the gate tile is waited for at its first use
# baseline (speedup 1.0000x reference)
.LBB0_220:
	s_waitcnt vmcnt(9)
	v_add_u32_e32 v0, s19, v169
	v_ashrrev_i32_e32 v1, 31, v0
	v_readlane_b32 s0, v251, 24
	v_lshlrev_b64 v[108:109], 12, v[0:1]
	v_readlane_b32 s1, v251, 25
	s_ashr_i32 s35, s34, 31
	v_readlane_b32 s40, v254, 20
	v_lshl_add_u64 v[0:1], s[0:1], 0, v[108:109]
	s_lshl_b32 s28, s17, 1
	s_lshl_b64 s[0:1], s[34:35], 2
	v_readlane_b32 s50, v254, 30
	v_lshl_add_u64 v[0:1], v[0:1], 0, s[28:29]
	v_mov_b32_e32 v133, v157
	v_readlane_b32 s51, v254, 31
	s_add_u32 s0, s50, s0
	v_lshl_add_u64 v[0:1], v[0:1], 0, v[132:133]
	s_addc_u32 s1, s51, s1
	global_load_dword v110, v157, s[0:1]
	global_load_dwordx4 v[28:31], v[0:1], off
	global_load_dwordx4 v[24:27], v[0:1], off offset:128
	global_load_dwordx4 v[20:23], v[0:1], off offset:256
	global_load_dwordx4 v[16:19], v[0:1], off offset:384
	global_load_dwordx4 v[12:15], v[0:1], off offset:512
	global_load_dwordx4 v[8:11], v[0:1], off offset:640
	global_load_dwordx4 v[4:7], v[0:1], off offset:768
	s_nop 0
	global_load_dwordx4 v[0:3], v[0:1], off offset:896
	v_cmp_lt_i32_e32 vcc, v188, v187
	v_readlane_b32 s0, v253, 62
	s_mov_b32 s56, 0x800000
	v_readlane_b32 s52, v254, 32
	v_add3_u32 v112, s0, v173, v137
	ds_read2_b64 v[104:107], v112 offset1:4
	v_add_u32_e32 v113, 0x1000, v112
	v_add_u32_e32 v118, 0x1800, v112
	s_lshl_b32 s0, s20, 2
	s_add_i32 s0, s0, 16
	s_waitcnt vmcnt(10) lgkmcnt(0)
	v_lshlrev_b32_e32 v32, 16, v104
	v_readlane_b32 s53, v254, 33
	v_readlane_b32 s8, v251, 51
	v_readlane_b32 s9, v251, 52
	v_readlane_b32 s72, v254, 41
	v_readlane_b32 s54, v254, 34
	v_readlane_b32 s55, v254, 35
	v_readlane_b32 s70, v254, 39
	v_readlane_b32 s73, v254, 42
	v_readlane_b32 s74, v254, 44
	v_readlane_b32 s76, v254, 46
	v_readlane_b32 s78, v254, 48
	v_readlane_b32 s82, v254, 52
	v_readlane_b32 s60, v254, 54
	v_readlane_b32 s62, v254, 56
	v_readlane_b32 s64, v254, 58
	v_readlane_b32 s66, v254, 60
	s_movk_i32 s68, 0x2040
	v_readlane_b32 s57, v254, 36
	v_readlane_b32 s58, v254, 37
	v_readlane_b32 s59, v254, 38
	v_readlane_b32 s71, v254, 40
	v_readlane_b32 s69, v254, 43
	v_readlane_b32 s75, v254, 45
	v_readlane_b32 s77, v254, 47
	v_readlane_b32 s79, v254, 49
	v_readlane_b32 s80, v254, 50
	v_readlane_b32 s81, v254, 51
	v_readlane_b32 s83, v254, 53
	v_readlane_b32 s61, v254, 55
	v_readlane_b32 s63, v254, 57
	v_readlane_b32 s65, v254, 59
	v_readlane_b32 s67, v254, 61
	s_movk_i32 s73, 0xf5
	s_movk_i32 s55, 0xfff
	s_mov_b32 s54, 0xf0c0
	v_readlane_b32 s41, v254, 21
	v_readlane_b32 s42, v254, 22
	v_readlane_b32 s43, v254, 23
	v_readlane_b32 s44, v254, 24
	v_readlane_b32 s45, v254, 25
	v_readlane_b32 s46, v254, 26
	v_readlane_b32 s47, v254, 27
	v_readlane_b32 s48, v254, 28
	v_readlane_b32 s49, v254, 29
	s_waitcnt vmcnt(8)
	v_fma_f32 v111, v110, v32, v40
	v_and_b32_e32 v32, 0xffff0000, v104
	v_fma_f32 v104, v110, v32, v41
	v_lshlrev_b32_e32 v32, 16, v105
	v_fma_f32 v42, v110, v32, v42
	v_and_b32_e32 v32, 0xffff0000, v105
	v_add_u32_e32 v105, 0x800, v112
	ds_read2_b64 v[34:37], v105 offset0:32 offset1:36
	ds_read2_b64 v[38:41], v113 offset0:64 offset1:68
	v_fmac_f32_e32 v43, v110, v32
	ds_read2_b64 v[114:117], v105 offset0:40 offset1:44
	s_waitcnt lgkmcnt(2)
	v_lshlrev_b32_e32 v32, 16, v34
	v_fma_f32 v48, v110, v32, v48
	v_and_b32_e32 v32, 0xffff0000, v34
	v_fma_f32 v49, v110, v32, v49
	v_lshlrev_b32_e32 v32, 16, v35
	v_fma_f32 v50, v110, v32, v50
	v_and_b32_e32 v32, 0xffff0000, v35
	v_fmac_f32_e32 v51, v110, v32
	s_waitcnt lgkmcnt(1)
	v_lshlrev_b32_e32 v32, 16, v38
	v_fma_f32 v44, v110, v32, v44
	v_and_b32_e32 v32, 0xffff0000, v38
	v_fma_f32 v38, v110, v32, v45
	v_lshlrev_b32_e32 v32, 16, v39
	v_fma_f32 v45, v110, v32, v46
	v_and_b32_e32 v32, 0xffff0000, v39
	v_fmac_f32_e32 v47, v110, v32
	ds_read2_b64 v[32:35], v118 offset0:96 offset1:100
	ds_read2_b64 v[118:121], v118 offset0:104 offset1:108
	s_waitcnt lgkmcnt(1)
	v_lshlrev_b32_e32 v46, 16, v33
	v_fma_f32 v46, v110, v46, v54
	v_and_b32_e32 v33, 0xffff0000, v33
	v_and_b32_e32 v54, 0xffff0000, v107
	v_lshlrev_b32_e32 v39, 16, v32
	v_fmac_f32_e32 v55, v110, v33
	v_lshlrev_b32_e32 v33, 16, v106
	v_fmac_f32_e32 v59, v110, v54
	v_lshlrev_b32_e32 v54, 16, v36
	v_and_b32_e32 v36, 0xffff0000, v36
	v_fma_f32 v39, v110, v39, v52
	v_fma_f32 v33, v110, v33, v56
	v_and_b32_e32 v52, 0xffff0000, v106
	v_fma_f32 v56, v110, v36, v61
	v_lshlrev_b32_e32 v36, 16, v37
	v_and_b32_e32 v32, 0xffff0000, v32
	v_fma_f32 v52, v110, v52, v57
	v_fma_f32 v57, v110, v36, v62
	v_and_b32_e32 v36, 0xffff0000, v37
	v_fma_f32 v32, v110, v32, v53
	v_lshlrev_b32_e32 v53, 16, v107
	v_fmac_f32_e32 v63, v110, v36
	v_lshlrev_b32_e32 v36, 16, v40
	v_fma_f32 v53, v110, v53, v58
	v_fma_f32 v58, v110, v36, v64
	v_and_b32_e32 v36, 0xffff0000, v40
	v_fma_f32 v40, v110, v36, v65
	v_lshlrev_b32_e32 v36, 16, v41
	v_fma_f32 v54, v110, v54, v60
	v_fma_f32 v60, v110, v36, v66
	v_and_b32_e32 v36, 0xffff0000, v41
	v_fmac_f32_e32 v67, v110, v36
	v_lshlrev_b32_e32 v36, 16, v34
	v_and_b32_e32 v34, 0xffff0000, v34
	v_fma_f32 v61, v110, v34, v81
	v_lshlrev_b32_e32 v34, 16, v35
	v_fma_f32 v62, v110, v34, v82
	v_and_b32_e32 v34, 0xffff0000, v35
	v_fma_f32 v41, v110, v36, v80
	v_fmac_f32_e32 v83, v110, v34
	ds_read2_b64 v[34:37], v112 offset0:8 offset1:12
	v_and_b32_e32 v66, 0xffff0000, v114
	v_fma_f32 v66, v110, v66, v73
	v_and_b32_e32 v73, 0xffff0000, v115
	v_and_b32_e32 v80, 0xffff0000, v116
	s_waitcnt lgkmcnt(0)
	v_lshlrev_b32_e32 v65, 16, v35
	v_fma_f32 v65, v110, v65, v78
	v_lshlrev_b32_e32 v78, 16, v37
	v_fma_f32 v78, v110, v78, v90
	v_and_b32_e32 v37, 0xffff0000, v37
	v_and_b32_e32 v90, 0xffff0000, v121
	v_and_b32_e32 v35, 0xffff0000, v35
	v_fmac_f32_e32 v91, v110, v37
	v_lshlrev_b32_e32 v37, 16, v116
	v_fmac_f32_e32 v103, v110, v90
	v_lshl_add_u32 v90, v171, 2, s0
	s_movk_i32 s0, 0x2040
	v_fmac_f32_e32 v79, v110, v35
	v_lshlrev_b32_e32 v35, 16, v114
	v_fma_f32 v37, v110, v37, v92
	v_mad_u32_u24 v92, v172, s0, v90
	v_fma_f32 v35, v110, v35, v72
	v_lshlrev_b32_e32 v72, 16, v115
	ds_read2_b64 v[112:115], v113 offset0:72 offset1:76
	s_waitcnt lgkmcnt(0)
	s_barrier
	ds_write2_b32 v92, v111, v48 offset1:16
	v_add_u32_e32 v48, 0x800, v92
	ds_write2_b32 v48, v104, v49 offset0:4 offset1:20
	v_add_u32_e32 v49, 0x1000, v92
	ds_write2_b32 v49, v42, v50 offset0:8 offset1:24
	v_add_u32_e32 v42, 0x1800, v92
	ds_write2_b32 v42, v43, v51 offset0:12 offset1:28
	ds_write2_b32 v92, v44, v39 offset0:32 offset1:48
	ds_write2_b32 v48, v38, v32 offset0:36 offset1:52
	ds_write2_b32 v49, v45, v46 offset0:40 offset1:56
	ds_write2_b32 v42, v47, v55 offset0:44 offset1:60
	v_add_u32_e32 v32, 0x8000, v92
	ds_write2_b32 v32, v33, v54 offset0:64 offset1:80
	v_add_u32_e32 v33, 0x8800, v92
	v_add_u32_e32 v38, 0x9000, v92
	v_add_u32_e32 v39, 0x9800, v92
	ds_write2_b32 v33, v52, v56 offset0:68 offset1:84
	ds_write2_b32 v38, v53, v57 offset0:72 offset1:88
	ds_write2_b32 v39, v59, v63 offset0:76 offset1:92
	ds_write2_b32 v32, v58, v41 offset0:96 offset1:112
	ds_write2_b32 v33, v40, v61 offset0:100 offset1:116
	ds_write2_b32 v38, v60, v62 offset0:104 offset1:120
	ds_write2_b32 v39, v67, v83 offset0:108 offset1:124
	v_mov_b32_e32 v32, 0x10200
	v_lshlrev_b32_e32 v64, 16, v34
	v_mad_u32_u24 v32, v172, s0, v32
	v_fma_f32 v64, v110, v64, v76
	v_add_u32_e32 v33, v90, v32
	ds_write_b32 v33, v64
	v_mov_b32_e32 v33, 0x10a10
	v_and_b32_e32 v34, 0xffff0000, v34
	v_mad_u32_u24 v33, v172, s0, v33
	v_fma_f32 v34, v110, v34, v77
	v_add_u32_e32 v38, v90, v33
	ds_write_b32 v38, v34
	v_mov_b32_e32 v34, 0x11220
	v_mad_u32_u24 v34, v172, s0, v34
	v_add_u32_e32 v38, v90, v34
	ds_write_b32 v38, v65
	v_mov_b32_e32 v38, 0x11a30
	v_mad_u32_u24 v38, v172, s0, v38
	v_fmac_f32_e32 v75, v110, v73
	v_lshlrev_b32_e32 v73, 16, v112
	v_fma_f32 v80, v110, v80, v93
	v_add_u32_e32 v93, 64, v90
	v_add_u32_e32 v39, v90, v38
	v_fma_f32 v68, v110, v73, v68
	v_and_b32_e32 v73, 0xffff0000, v112
	ds_write_b32 v39, v79
	v_add_u32_e32 v39, v93, v32
	v_fma_f32 v69, v110, v73, v69
	v_lshlrev_b32_e32 v73, 16, v113
	ds_write_b32 v39, v35
	v_add_u32_e32 v35, v93, v33
	v_fma_f32 v72, v110, v72, v74
	v_fma_f32 v70, v110, v73, v70
	v_and_b32_e32 v73, 0xffff0000, v113
	ds_write_b32 v35, v66
	v_add_u32_e32 v35, v93, v34
	v_fmac_f32_e32 v71, v110, v73
	v_lshlrev_b32_e32 v73, 16, v118
	v_add_u32_e32 v43, 0x80, v90
	v_add_u32_e32 v50, 0xc0, v90
	ds_write_b32 v35, v72
	v_add_u32_e32 v35, v93, v38
	v_fma_f32 v73, v110, v73, v84
	v_and_b32_e32 v74, 0xffff0000, v118
	ds_write_b32 v35, v75
	v_add_u32_e32 v35, v43, v32
	v_add_u32_e32 v32, v50, v32
	v_fma_f32 v74, v110, v74, v85
	v_lshlrev_b32_e32 v76, 16, v119
	ds_write_b32 v32, v73
	v_add_u32_e32 v32, v50, v33
	v_fma_f32 v76, v110, v76, v86
	v_and_b32_e32 v77, 0xffff0000, v119
	ds_write_b32 v32, v74
	v_add_u32_e32 v32, v50, v34
	v_fmac_f32_e32 v87, v110, v77
	ds_write_b32 v32, v76
	v_add_u32_e32 v32, v50, v38
	ds_write_b32 v32, v87
	v_mov_b32_e32 v32, 0x18300
	v_lshlrev_b32_e32 v77, 16, v36
	v_mad_u32_u24 v32, v172, s0, v32
	v_fma_f32 v77, v110, v77, v88
	ds_write_b32 v35, v68
	v_add_u32_e32 v35, v43, v33
	v_add_u32_e32 v33, v90, v32
	ds_write_b32 v33, v77
	v_mov_b32_e32 v33, 0x18b10
	v_and_b32_e32 v36, 0xffff0000, v36
	v_mad_u32_u24 v33, v172, s0, v33
	v_fma_f32 v36, v110, v36, v89
	ds_write_b32 v35, v69
	v_add_u32_e32 v35, v43, v34
	v_add_u32_e32 v34, v90, v33
	ds_write_b32 v34, v36
	v_mov_b32_e32 v34, 0x19320
	ds_write_b32 v35, v70
	v_add_u32_e32 v35, v43, v38
	v_mad_u32_u24 v34, v172, s0, v34
	ds_write_b32 v35, v71
	v_add_u32_e32 v35, v90, v34
	ds_write_b32 v35, v78
	v_mad_u32_u24 v35, v172, s0, v198
	v_add_u32_e32 v36, v90, v35
	ds_write_b32 v36, v91
	v_add_u32_e32 v36, v93, v32
	v_lshlrev_b32_e32 v81, 16, v117
	ds_write_b32 v36, v37
	v_add_u32_e32 v36, v93, v33
	v_fma_f32 v81, v110, v81, v94
	v_and_b32_e32 v82, 0xffff0000, v117
	v_and_b32_e32 v86, 0xffff0000, v115
	ds_write_b32 v36, v80
	v_add_u32_e32 v36, v93, v34
	v_fmac_f32_e32 v95, v110, v82
	v_fmac_f32_e32 v99, v110, v86
	v_lshlrev_b32_e32 v86, 16, v120
	ds_write_b32 v36, v81
	v_add_u32_e32 v36, v93, v35
	v_fma_f32 v86, v110, v86, v100
	v_and_b32_e32 v88, 0xffff0000, v120
	ds_write_b32 v36, v95
	v_add_u32_e32 v36, v43, v32
	v_add_u32_e32 v32, v50, v32
	v_lshlrev_b32_e32 v82, 16, v114
	v_fma_f32 v88, v110, v88, v101
	v_lshlrev_b32_e32 v89, 16, v121
	ds_write_b32 v32, v86
	v_add_u32_e32 v32, v50, v33
	v_fma_f32 v82, v110, v82, v96
	v_and_b32_e32 v84, 0xffff0000, v114
	v_fma_f32 v89, v110, v89, v102
	ds_write_b32 v32, v88
	v_add_u32_e32 v32, v50, v34
	v_fma_f32 v84, v110, v84, v97
	v_lshlrev_b32_e32 v85, 16, v115
	ds_write_b32 v36, v82
	v_add_u32_e32 v36, v43, v33
	ds_write_b32 v32, v89
	v_add_u32_e32 v32, v50, v35
	s_movk_i32 s0, 0x810
	v_fma_f32 v85, v110, v85, v98
	ds_write_b32 v36, v84
	v_add_u32_e32 v36, v43, v34
	ds_write_b32 v32, v103
	v_mul_lo_u32 v33, v169, s0
	v_lshlrev_b32_e32 v32, 2, v166
	ds_write_b32 v36, v85
	v_add_u32_e32 v36, v43, v35
	v_add3_u32 v76, 16, v33, v32
	ds_write_b32 v36, v99
	s_waitcnt lgkmcnt(0)
	s_barrier
	ds_read_b128 v[34:37], v76
	ds_read_b128 v[38:41], v76 offset:16
	s_waitcnt vmcnt(0)
	v_lshlrev_b32_e32 v33, 16, v28
	v_and_b32_e32 v28, 0xffff0000, v28
	v_lshlrev_b32_e32 v42, 16, v29
	s_waitcnt lgkmcnt(1)
	v_mul_f32_e32 v72, v35, v28
	v_mul_f32_e32 v73, v34, v33
	v_mul_f32_e32 v77, v72, v72
	v_and_b32_e32 v29, 0xffff0000, v29
	v_mul_f32_e32 v71, v36, v42
	v_fmac_f32_e32 v77, v73, v73
	v_lshlrev_b32_e32 v43, 16, v30
	v_and_b32_e32 v30, 0xffff0000, v30
	v_lshlrev_b32_e32 v44, 16, v31
	v_and_b32_e32 v31, 0xffff0000, v31
	v_mul_f32_e32 v70, v37, v29
	v_fmac_f32_e32 v77, v71, v71
	s_waitcnt lgkmcnt(0)
	v_mul_f32_e32 v69, v38, v43
	v_mul_f32_e32 v68, v39, v30
	v_mul_f32_e32 v65, v41, v31
	v_fmac_f32_e32 v77, v70, v70
	ds_read_b128 v[28:31], v76 offset:256
	ds_read_b128 v[34:37], v76 offset:272
	v_fmac_f32_e32 v77, v69, v69
	v_mul_f32_e32 v67, v40, v44
	v_fmac_f32_e32 v77, v68, v68
	v_fmac_f32_e32 v77, v67, v67
	v_lshlrev_b32_e32 v33, 16, v24
	v_fmac_f32_e32 v77, v65, v65
	v_and_b32_e32 v24, 0xffff0000, v24
	s_waitcnt lgkmcnt(1)
	v_mul_f32_e32 v66, v28, v33
	v_lshlrev_b32_e32 v38, 16, v25
	v_mul_f32_e32 v63, v29, v24
	v_fmac_f32_e32 v77, v66, v66
	v_and_b32_e32 v25, 0xffff0000, v25
	v_mul_f32_e32 v60, v30, v38
	v_fmac_f32_e32 v77, v63, v63
	v_lshlrev_b32_e32 v39, 16, v26
	v_and_b32_e32 v26, 0xffff0000, v26
	v_lshlrev_b32_e32 v40, 16, v27
	v_and_b32_e32 v27, 0xffff0000, v27
	v_mul_f32_e32 v56, v31, v25
	v_fmac_f32_e32 v77, v60, v60
	s_waitcnt lgkmcnt(0)
	v_mul_f32_e32 v51, v34, v39
	v_mul_f32_e32 v45, v35, v26
	v_mul_f32_e32 v35, v37, v27
	v_fmac_f32_e32 v77, v56, v56
	ds_read_b128 v[24:27], v76 offset:512
	ds_read_b128 v[28:31], v76 offset:528
	v_fmac_f32_e32 v77, v51, v51
	v_mul_f32_e32 v40, v36, v40
	v_fmac_f32_e32 v77, v45, v45
	v_fmac_f32_e32 v77, v40, v40
	v_lshlrev_b32_e32 v33, 16, v20
	v_fmac_f32_e32 v77, v35, v35
	v_and_b32_e32 v20, 0xffff0000, v20
	s_waitcnt lgkmcnt(1)
	v_mul_f32_e32 v64, v24, v33
	v_lshlrev_b32_e32 v34, 16, v21
	v_mul_f32_e32 v61, v25, v20
	v_fmac_f32_e32 v77, v64, v64
	v_and_b32_e32 v21, 0xffff0000, v21
	v_mul_f32_e32 v57, v26, v34
	v_fmac_f32_e32 v77, v61, v61
	v_lshlrev_b32_e32 v36, 16, v22
	v_and_b32_e32 v22, 0xffff0000, v22
	v_lshlrev_b32_e32 v37, 16, v23
	v_and_b32_e32 v23, 0xffff0000, v23
	v_mul_f32_e32 v52, v27, v21
	v_fmac_f32_e32 v77, v57, v57
	s_waitcnt lgkmcnt(0)
	v_mul_f32_e32 v46, v28, v36
	v_mul_f32_e32 v41, v29, v22
	v_mul_f32_e32 v36, v30, v37
	v_mul_f32_e32 v30, v31, v23
	v_fmac_f32_e32 v77, v52, v52
	ds_read_b128 v[20:23], v76 offset:768
	ds_read_b128 v[24:27], v76 offset:784
	v_fmac_f32_e32 v77, v46, v46
	v_fmac_f32_e32 v77, v41, v41
	v_fmac_f32_e32 v77, v36, v36
	v_lshlrev_b32_e32 v28, 16, v16
	v_fmac_f32_e32 v77, v30, v30
	v_and_b32_e32 v16, 0xffff0000, v16
	s_waitcnt lgkmcnt(1)
	v_mul_f32_e32 v62, v20, v28
	v_lshlrev_b32_e32 v29, 16, v17
	v_mul_f32_e32 v58, v21, v16
	v_fmac_f32_e32 v77, v62, v62
	v_and_b32_e32 v17, 0xffff0000, v17
	v_mul_f32_e32 v53, v22, v29
	v_fmac_f32_e32 v77, v58, v58
	v_lshlrev_b32_e32 v31, 16, v18
	v_and_b32_e32 v18, 0xffff0000, v18
	v_lshlrev_b32_e32 v33, 16, v19
	v_and_b32_e32 v19, 0xffff0000, v19
	v_mul_f32_e32 v47, v23, v17
	v_fmac_f32_e32 v77, v53, v53
	s_waitcnt lgkmcnt(0)
	v_mul_f32_e32 v42, v24, v31
	v_mul_f32_e32 v37, v25, v18
	v_mul_f32_e32 v27, v27, v19
	v_fmac_f32_e32 v77, v47, v47
	ds_read_b128 v[16:19], v76 offset:1024
	ds_read_b128 v[20:23], v76 offset:1040
	v_fmac_f32_e32 v77, v42, v42
	v_mul_f32_e32 v31, v26, v33
	v_fmac_f32_e32 v77, v37, v37
	v_fmac_f32_e32 v77, v31, v31
	v_lshlrev_b32_e32 v24, 16, v12
	v_fmac_f32_e32 v77, v27, v27
	v_and_b32_e32 v12, 0xffff0000, v12
	s_waitcnt lgkmcnt(1)
	v_mul_f32_e32 v59, v16, v24
	v_lshlrev_b32_e32 v25, 16, v13
	v_mul_f32_e32 v54, v17, v12
	v_fmac_f32_e32 v77, v59, v59
	v_and_b32_e32 v13, 0xffff0000, v13
	v_mul_f32_e32 v48, v18, v25
	v_fmac_f32_e32 v77, v54, v54
	v_lshlrev_b32_e32 v26, 16, v14
	v_and_b32_e32 v14, 0xffff0000, v14
	v_lshlrev_b32_e32 v28, 16, v15
	v_and_b32_e32 v15, 0xffff0000, v15
	v_mul_f32_e32 v43, v19, v13
	v_fmac_f32_e32 v77, v48, v48
	s_waitcnt lgkmcnt(0)
	v_mul_f32_e32 v38, v20, v26
	v_mul_f32_e32 v33, v21, v14
	v_mul_f32_e32 v24, v23, v15
	v_fmac_f32_e32 v77, v43, v43
	ds_read_b128 v[12:15], v76 offset:1280
	ds_read_b128 v[16:19], v76 offset:1296
	v_fmac_f32_e32 v77, v38, v38
	v_mul_f32_e32 v28, v22, v28
	v_fmac_f32_e32 v77, v33, v33
	v_fmac_f32_e32 v77, v28, v28
	v_lshlrev_b32_e32 v20, 16, v8
	v_fmac_f32_e32 v77, v24, v24
	v_and_b32_e32 v8, 0xffff0000, v8
	s_waitcnt lgkmcnt(1)
	v_mul_f32_e32 v55, v12, v20
	v_lshlrev_b32_e32 v21, 16, v9
	v_mul_f32_e32 v49, v13, v8
	v_fmac_f32_e32 v77, v55, v55
	v_and_b32_e32 v9, 0xffff0000, v9
	v_mul_f32_e32 v44, v14, v21
	v_fmac_f32_e32 v77, v49, v49
	v_lshlrev_b32_e32 v22, 16, v10
	v_and_b32_e32 v10, 0xffff0000, v10
	v_lshlrev_b32_e32 v23, 16, v11
	v_and_b32_e32 v11, 0xffff0000, v11
	v_mul_f32_e32 v39, v15, v9
	v_fmac_f32_e32 v77, v44, v44
	s_waitcnt lgkmcnt(0)
	v_mul_f32_e32 v34, v16, v22
	v_mul_f32_e32 v29, v17, v10
	v_mul_f32_e32 v25, v18, v23
	v_mul_f32_e32 v23, v19, v11
	v_fmac_f32_e32 v77, v39, v39
	ds_read_b128 v[8:11], v76 offset:1536
	ds_read_b128 v[12:15], v76 offset:1552
	v_fmac_f32_e32 v77, v34, v34
	v_fmac_f32_e32 v77, v29, v29
	v_fmac_f32_e32 v77, v25, v25
	v_lshlrev_b32_e32 v16, 16, v4
	v_fmac_f32_e32 v77, v23, v23
	v_and_b32_e32 v4, 0xffff0000, v4
	s_waitcnt lgkmcnt(1)
	v_mul_f32_e32 v50, v8, v16
	v_lshlrev_b32_e32 v17, 16, v5
	v_and_b32_e32 v5, 0xffff0000, v5
	v_lshlrev_b32_e32 v18, 16, v6
	v_and_b32_e32 v6, 0xffff0000, v6
	v_lshlrev_b32_e32 v74, 16, v7
	v_and_b32_e32 v7, 0xffff0000, v7
	v_mul_f32_e32 v26, v9, v4
	v_fmac_f32_e32 v77, v50, v50
	v_mul_f32_e32 v22, v10, v17
	v_mul_f32_e32 v21, v11, v5
	s_waitcnt lgkmcnt(0)
	v_mul_f32_e32 v20, v12, v18
	v_mul_f32_e32 v19, v13, v6
	v_mul_f32_e32 v18, v14, v74
	v_mul_f32_e32 v17, v15, v7
	v_fmac_f32_e32 v77, v26, v26
	v_lshlrev_b32_e32 v4, 16, v0
	v_and_b32_e32 v5, 0xffff0000, v0
	v_lshlrev_b32_e32 v6, 16, v1
	v_and_b32_e32 v7, 0xffff0000, v1
	v_lshlrev_b32_e32 v8, 16, v2
	v_and_b32_e32 v9, 0xffff0000, v2
	v_lshlrev_b32_e32 v74, 16, v3
	v_and_b32_e32 v75, 0xffff0000, v3
	ds_read_b128 v[0:3], v76 offset:1792
	v_fmac_f32_e32 v77, v22, v22
	v_fmac_f32_e32 v77, v21, v21
	v_fmac_f32_e32 v77, v20, v20
	v_fmac_f32_e32 v77, v19, v19
	v_fmac_f32_e32 v77, v18, v18
	s_waitcnt lgkmcnt(0)
	v_pk_mul_f32 v[14:15], v[0:1], v[4:5]
	v_fmac_f32_e32 v77, v17, v17
	v_pk_mul_f32 v[0:1], v[14:15], v[14:15]
	v_pk_mul_f32 v[12:13], v[2:3], v[6:7]
	v_add_f32_e32 v0, v77, v0
	v_add_f32_e32 v4, v0, v1
	v_pk_mul_f32 v[0:1], v[12:13], v[12:13]
	s_lshl_b32 s0, s17, 2
	v_add_f32_e32 v0, v4, v0
	v_add_f32_e32 v4, v0, v1
	ds_read_b128 v[0:3], v76 offset:1808
	s_add_u32 s0, s52, s0
	s_addc_u32 s1, s53, 0
	s_waitcnt lgkmcnt(0)
	v_pk_mul_f32 v[10:11], v[0:1], v[8:9]
	s_nop 0
	v_pk_mul_f32 v[0:1], v[10:11], v[10:11]
	v_pk_mul_f32 v[8:9], v[2:3], v[74:75]
	v_add_f32_e32 v0, v4, v0
	v_add_f32_e32 v4, v0, v1
	v_pk_mul_f32 v[0:1], v[8:9], v[8:9]
	s_nop 0
	v_add_f32_e32 v0, v4, v0
	v_add_f32_e32 v0, v0, v1
	v_cndmask_b32_e32 v1, v185, v188, vcc
	v_lshlrev_b32_e32 v1, 2, v1
	ds_bpermute_b32 v1, v1, v0
	v_cmp_lt_i32_e32 vcc, v189, v187
	s_waitcnt lgkmcnt(0)
	v_add_f32_e32 v0, v0, v1
	v_cndmask_b32_e32 v1, v185, v189, vcc
	v_lshlrev_b32_e32 v1, 2, v1
	ds_bpermute_b32 v1, v1, v0
	v_cmp_lt_i32_e32 vcc, v190, v187
	s_waitcnt lgkmcnt(0)
	v_add_f32_e32 v0, v0, v1
	v_cndmask_b32_e32 v1, v185, v190, vcc
	v_lshlrev_b32_e32 v1, 2, v1
	ds_bpermute_b32 v1, v1, v0
	s_waitcnt lgkmcnt(0)
	v_add_f32_e32 v0, v0, v1
	v_fmamk_f32 v0, v0, 0x3b000000, v182
	v_cmp_gt_f32_e32 vcc, s56, v0
	v_mul_f32_e32 v1, 0x4b800000, v0
	s_nop 0
	v_cndmask_b32_e32 v0, v0, v1, vcc
	v_rsq_f32_e32 v0, v0
	s_nop 0
	v_mul_f32_e32 v1, 0x45800000, v0
	v_cndmask_b32_e32 v16, v0, v1, vcc
	global_load_dwordx4 v[74:77], v32, s[0:1] offset:16
	global_load_dwordx4 v[78:81], v32, s[0:1]
	global_load_dwordx4 v[82:85], v32, s[0:1] offset:272
	global_load_dwordx4 v[86:89], v32, s[0:1] offset:256
	global_load_dwordx4 v[90:93], v32, s[0:1] offset:528
	global_load_dwordx4 v[94:97], v32, s[0:1] offset:512
	global_load_dwordx4 v[98:101], v32, s[0:1] offset:784
	global_load_dwordx4 v[102:105], v32, s[0:1] offset:768
	global_load_dwordx4 v[110:113], v32, s[0:1] offset:1040
	global_load_dwordx4 v[114:117], v32, s[0:1] offset:1024
	global_load_dwordx4 v[118:121], v32, s[0:1] offset:1296
	global_load_dwordx4 v[122:125], v32, s[0:1] offset:1280
	global_load_dwordx4 v[126:129], v32, s[0:1] offset:1552
	global_load_dwordx4 v[134:137], v32, s[0:1] offset:1536
	global_load_dwordx4 v[138:141], v32, s[0:1] offset:1808
	global_load_dwordx4 v[142:145], v32, s[0:1] offset:1792
	v_mul_f32_e32 v73, v73, v16
	v_mul_f32_e32 v69, v69, v16
	v_mul_f32_e32 v68, v68, v16
	v_mul_f32_e32 v67, v67, v16
	v_mul_f32_e32 v72, v72, v16
	v_mul_f32_e32 v71, v71, v16
	v_mul_f32_e32 v70, v70, v16
	v_mul_f32_e32 v51, v51, v16
	v_mul_f32_e32 v60, v60, v16
	v_mul_f32_e32 v56, v56, v16
	v_mul_f32_e32 v20, v20, v16
	v_mul_f32_e32 v22, v22, v16
	v_mul_f32_e32 v21, v21, v16
	v_mul_f32_e32 v10, v10, v16
	v_mul_f32_e32 v12, v12, v16
	v_mul_f32_e32 v13, v13, v16
	s_waitcnt vmcnt(15)
	v_mul_f32_e32 v0, v74, v69
	s_waitcnt vmcnt(14)
	v_mul_f32_e32 v4, v78, v73
	v_mul_f32_e32 v1, v75, v68
	v_mul_f32_e32 v67, v76, v67
	v_mul_f32_e32 v2, v65, v16
	v_mul_f32_e32 v5, v79, v72
	v_mul_f32_e32 v65, v77, v2
	v_cvt_pk_bf16_f32 v2, v4, v5
	v_cvt_pk_bf16_f32 v4, v0, v1
	v_lshl_add_u64 v[0:1], s[8:9], 0, v[108:109]
	v_lshl_add_u64 v[0:1], v[0:1], 0, s[28:29]
	v_lshl_add_u64 v[0:1], v[0:1], 0, v[132:133]
	v_mul_f32_e32 v6, v80, v71
	v_mul_f32_e32 v7, v81, v70
	v_cvt_pk_bf16_f32 v3, v6, v7
	v_cvt_pk_bf16_f32 v5, v67, v65
	global_store_dwordx4 v[0:1], v[2:5], off
	v_mul_f32_e32 v6, v66, v16
	v_mul_f32_e32 v7, v63, v16
	s_waitcnt vmcnt(14)
	v_mul_f32_e32 v51, v51, v82
	v_mul_f32_e32 v2, v45, v16
	v_mul_f32_e32 v45, v2, v83
	v_mul_f32_e32 v2, v40, v16
	v_mul_f32_e32 v40, v2, v84
	v_mul_f32_e32 v2, v35, v16
	v_mul_f32_e32 v5, v2, v85
	s_waitcnt vmcnt(13)
	v_mul_f32_e32 v6, v6, v86
	v_mul_f32_e32 v7, v7, v87
	v_mul_f32_e32 v60, v60, v88
	v_mul_f32_e32 v56, v56, v89
	v_cvt_pk_bf16_f32 v2, v6, v7
	v_cvt_pk_bf16_f32 v3, v60, v56
	v_cvt_pk_bf16_f32 v4, v51, v45
	v_cvt_pk_bf16_f32 v5, v40, v5
	global_store_dwordx4 v[0:1], v[2:5], off offset:128
	v_mul_f32_e32 v45, v46, v16
	v_mul_f32_e32 v6, v64, v16
	v_mul_f32_e32 v7, v61, v16
	v_mul_f32_e32 v35, v57, v16
	v_mul_f32_e32 v40, v52, v16
	s_waitcnt vmcnt(13)
	v_mul_f32_e32 v45, v45, v90
	v_mul_f32_e32 v2, v41, v16
	v_mul_f32_e32 v41, v2, v91
	v_mul_f32_e32 v2, v36, v16
	v_mul_f32_e32 v36, v2, v92
	v_mul_f32_e32 v2, v30, v16
	v_mul_f32_e32 v5, v2, v93
	s_waitcnt vmcnt(12)
	v_mul_f32_e32 v6, v6, v94
	v_mul_f32_e32 v7, v7, v95
	v_mul_f32_e32 v35, v35, v96
	v_mul_f32_e32 v40, v40, v97
	v_cvt_pk_bf16_f32 v2, v6, v7
	v_cvt_pk_bf16_f32 v3, v35, v40
	v_cvt_pk_bf16_f32 v4, v45, v41
	v_cvt_pk_bf16_f32 v5, v36, v5
	global_store_dwordx4 v[0:1], v[2:5], off offset:256
	v_mul_f32_e32 v36, v42, v16
	v_mul_f32_e32 v6, v62, v16
	v_mul_f32_e32 v7, v58, v16
	v_mul_f32_e32 v30, v53, v16
	v_mul_f32_e32 v35, v47, v16
	s_waitcnt vmcnt(12)
	v_mul_f32_e32 v36, v36, v98
	v_mul_f32_e32 v2, v37, v16
	v_mul_f32_e32 v37, v2, v99
	v_mul_f32_e32 v2, v31, v16
	v_mul_f32_e32 v31, v2, v100
	v_mul_f32_e32 v2, v27, v16
	v_mul_f32_e32 v5, v2, v101
	s_waitcnt vmcnt(11)
	v_mul_f32_e32 v6, v6, v102
	v_mul_f32_e32 v7, v7, v103
	v_mul_f32_e32 v30, v30, v104
	v_mul_f32_e32 v35, v35, v105
	v_cvt_pk_bf16_f32 v2, v6, v7
	v_cvt_pk_bf16_f32 v3, v30, v35
	v_cvt_pk_bf16_f32 v4, v36, v37
	v_cvt_pk_bf16_f32 v5, v31, v5
	global_store_dwordx4 v[0:1], v[2:5], off offset:384
	v_mul_f32_e32 v31, v38, v16
	v_mul_f32_e32 v6, v59, v16
	v_mul_f32_e32 v7, v54, v16
	v_mul_f32_e32 v27, v48, v16
	v_mul_f32_e32 v30, v43, v16
	s_waitcnt vmcnt(11)
	v_mul_f32_e32 v31, v31, v110
	v_mul_f32_e32 v2, v33, v16
	v_mul_f32_e32 v33, v2, v111
	v_mul_f32_e32 v2, v28, v16
	v_mul_f32_e32 v28, v2, v112
	v_mul_f32_e32 v2, v24, v16
	v_mul_f32_e32 v5, v2, v113
	s_waitcnt vmcnt(10)
	v_mul_f32_e32 v6, v6, v114
	v_mul_f32_e32 v7, v7, v115
	v_mul_f32_e32 v27, v27, v116
	v_mul_f32_e32 v30, v30, v117
	v_cvt_pk_bf16_f32 v2, v6, v7
	v_cvt_pk_bf16_f32 v3, v27, v30
	v_cvt_pk_bf16_f32 v4, v31, v33
	v_cvt_pk_bf16_f32 v5, v28, v5
	global_store_dwordx4 v[0:1], v[2:5], off offset:512
	v_mul_f32_e32 v28, v34, v16
	v_mul_f32_e32 v6, v55, v16
	v_mul_f32_e32 v7, v49, v16
	v_mul_f32_e32 v24, v44, v16
	v_mul_f32_e32 v27, v39, v16
	s_waitcnt vmcnt(10)
	v_mul_f32_e32 v28, v28, v118
	v_mul_f32_e32 v2, v29, v16
	v_mul_f32_e32 v29, v2, v119
	v_mul_f32_e32 v2, v25, v16
	v_mul_f32_e32 v25, v2, v120
	v_mul_f32_e32 v2, v23, v16
	v_mul_f32_e32 v5, v2, v121
	s_waitcnt vmcnt(9)
	v_mul_f32_e32 v6, v6, v122
	v_mul_f32_e32 v7, v7, v123
	v_mul_f32_e32 v24, v24, v124
	v_mul_f32_e32 v27, v27, v125
	v_cvt_pk_bf16_f32 v2, v6, v7
	v_cvt_pk_bf16_f32 v3, v24, v27
	v_cvt_pk_bf16_f32 v4, v28, v29
	v_cvt_pk_bf16_f32 v5, v25, v5
	global_store_dwordx4 v[0:1], v[2:5], off offset:640
	v_mul_f32_e32 v6, v50, v16
	v_mul_f32_e32 v7, v26, v16
	s_waitcnt vmcnt(9)
	v_mul_f32_e32 v20, v20, v126
	v_mul_f32_e32 v2, v19, v16
	v_mul_f32_e32 v19, v2, v127
	v_mul_f32_e32 v2, v18, v16
	v_mul_f32_e32 v18, v2, v128
	v_mul_f32_e32 v2, v17, v16
	v_mul_f32_e32 v5, v2, v129
	s_waitcnt vmcnt(8)
	v_mul_f32_e32 v6, v6, v134
	v_mul_f32_e32 v7, v7, v135
	v_mul_f32_e32 v22, v22, v136
	v_mul_f32_e32 v21, v21, v137
	v_cvt_pk_bf16_f32 v2, v6, v7
	v_cvt_pk_bf16_f32 v3, v22, v21
	v_cvt_pk_bf16_f32 v4, v20, v19
	v_cvt_pk_bf16_f32 v5, v18, v5
	global_store_dwordx4 v[0:1], v[2:5], off offset:768
	v_mul_f32_e32 v6, v14, v16
	v_mul_f32_e32 v7, v15, v16
	s_mov_b64 s[0:1], 0
	s_waitcnt vmcnt(8)
	v_mul_f32_e32 v10, v10, v138
	v_mul_f32_e32 v2, v11, v16
	v_mul_f32_e32 v11, v2, v139
	v_mul_f32_e32 v2, v8, v16
	v_mul_f32_e32 v8, v2, v140
	v_mul_f32_e32 v2, v9, v16
	v_mul_f32_e32 v5, v2, v141
	s_waitcnt vmcnt(7)
	v_mul_f32_e32 v6, v6, v142
	v_mul_f32_e32 v7, v7, v143
	v_mul_f32_e32 v12, v12, v144
	v_mul_f32_e32 v13, v13, v145
	v_cvt_pk_bf16_f32 v2, v6, v7
	v_cvt_pk_bf16_f32 v3, v12, v13
	v_cvt_pk_bf16_f32 v4, v10, v11
	v_cvt_pk_bf16_f32 v5, v8, v5
	global_store_dwordx4 v[0:1], v[2:5], off offset:896
	s_barrier
